# one static s_setprio 1 for waves 4-7 through the two MoBA attention phases (P4, P5), reset before the out-projection GEMM
# speedup vs baseline: 1.0016x; 1.0016x over previous
.LBB0_771:
	s_cmp_ge_u32 s73, 4
	s_cbranch_scc0 .Lmy_prio_a
	s_setprio 1

.LBB0_1179:
	s_setprio 0
	s_cmp_lt_i32 s74, 7
	s_cselect_b64 s[4:5], -1, 0
	s_and_b64 s[6:7], s[4:5], s[0:1]
	s_andn2_b64 vcc, exec, s[6:7]
	s_cbranch_vccnz .LBB0_1218
	s_and_b32 s4, s78, 0xffffffc0
	s_cmpk_lt_i32 s2, 0x400
	s_cselect_b64 s[0:1], -1, 0
	s_add_i32 s5, 0, 0x25000
	v_mov_b32_e32 v1, s5
	s_add_i32 s5, 0, 0x250a8
	ds_read_b64 v[2:3], v1
	v_mov_b32_e32 v1, s5
	ds_read_b64 v[4:5], v1
	v_mbcnt_lo_u32_b32 v0, -1, 0
	v_mbcnt_hi_u32_b32 v8, -1, v0
	v_add_u32_e32 v0, s4, v8
	s_waitcnt lgkmcnt(0)
	v_readfirstlane_b32 s9, v3
	v_readfirstlane_b32 s8, v2
	v_readfirstlane_b32 s5, v5
	v_readfirstlane_b32 s14, v4
	v_readfirstlane_b32 s4, v0
	s_and_b64 vcc, exec, s[0:1]
	s_cbranch_vccz .LBB0_1182
	s_ashr_i32 s10, s2, 31
	s_lshr_b32 s10, s10, 29
	s_add_i32 s10, s2, s10
	s_and_b32 s11, s10, -8
	s_sub_i32 s11, s2, s11
	s_lshl_b32 s13, s11, 7
	s_ashr_i32 s10, s10, 3
	s_mul_i32 s12, s11, 0x81
	s_cmp_lt_i32 s11, 0
	s_cselect_b32 s11, s12, s13
	s_add_i32 s10, s11, s10
	s_ashr_i32 s11, s10, 31
	s_lshr_b32 s11, s11, 26
	s_add_i32 s11, s10, s11
	s_ashr_i32 s12, s11, 6
	s_andn2_b32 s11, s11, 63
	s_sub_i32 s10, s10, s11
	s_bfe_i32 s11, s10, 0x80000
	s_bfe_u32 s11, s11, 0x3000c
	s_add_i32 s11, s10, s11
	s_bfe_i32 s13, s11, 0x80000
	s_and_b32 s11, s11, 0xf8
	s_sub_i32 s10, s10, s11
	s_lshl_b32 s12, s12, 3
	s_sext_i32_i16 s13, s13
	s_sext_i32_i8 s10, s10
	s_add_i32 s44, s12, s10
	s_ashr_i32 s42, s13, 3
